# 13 of 14 barriers XCD-local + consumer-side acquire (buffer_inv sc1) at the mixer>GEMM2 hand-off of the converted weights
# baseline (speedup 1.0000x reference)
; __global__ void __launch_bounds__(NWAVES * 64, 2) fwd_kernel(Args args) {
;     ...
;         if (ph + 1 < args.ph_hi || rep + 1 < nrep) { if (args.ph_hi > 1000) grid.sync(); else xcd_barrier(xb); } else __syncthreads();
cvx_wall_spin:
	global_load_dword v4, v3, s[22:23] offset:0 sc1
	global_load_dword v5, v3, s[22:23] offset:128 sc1
	global_load_dword v6, v3, s[22:23] offset:256 sc1
	global_load_dword v7, v3, s[22:23] offset:384 sc1
	global_load_dword v8, v3, s[22:23] offset:512 sc1
	global_load_dword v9, v3, s[22:23] offset:640 sc1
	global_load_dword v10, v3, s[22:23] offset:768 sc1
	global_load_dword v11, v3, s[22:23] offset:896 sc1
	s_waitcnt vmcnt(0)
	v_min_u32_e32 v4, v4, v5
	v_min_u32_e32 v6, v6, v7
	v_min_u32_e32 v8, v8, v9
	v_min_u32_e32 v10, v10, v11
	v_min_u32_e32 v4, v4, v6
	v_min_u32_e32 v8, v8, v10
	v_min_u32_e32 v4, v4, v8
	v_readfirstlane_b32 s34, v4
	s_nop 0
	s_cmp_ge_u32 s34, s3
	s_cbranch_scc1 cvx_wall_ok
	s_sleep 1
	s_add_i32 s2, s2, 1
	s_cmp_lt_u32 s2, 0x100000
	s_cbranch_scc1 cvx_wall_spin
cvx_wall_ok:
	buffer_inv sc1
	s_branch .LBB0_486
